# final: LDS-DMA K-loops for all five big GEMM families, XCD tile remap, K-buffer relocation (race fix), batched residual epilogue for ffn-down
# speedup vs baseline: 1.0074x; 1.0074x over previous
; #define MFMA32(a, b, c) __builtin_amdgcn_mfma_f32_32x32x16_bf16((a), (b), (c), 0, 0, 0)
; template <int MF, int BK, class Epi>
; DI void gemm_phase_t(char* lds, const GemmDesc g, const Epi epi) {
;     ...
;     for (int kt = 0; kt < nk; ++kt) {
;       __syncthreads();
;       const u16* sA = sbase + (kt & 1) * STG;
;       const u16* sB = sA + BM * LS;
;       if (kt + 1 < nk) {
;         u16* nA = sbase + ((kt + 1) & 1) * STG;
; #pragma unroll
;         for (int j = 0; j < APT; ++j) *(u32x4*)(nA + (lr + RSTEP * j) * LS + lc * 8) = ra[j];
; #pragma unroll
;         for (int j = 0; j < BPT; ++j) *(u32x4*)(nA + BM * LS + (lr + RSTEP * j) * LS + lc * 8) = rb[j];
;         if (kt + 2 < nk) {
; #pragma unroll
;           for (int j = 0; j < APT; ++j) ra[j] = *(const u32x4*)(Ap + (size_t)j * RSTEP * g.lda + (kt + 2) * BK);
; #pragma unroll
;           for (int j = 0; j < BPT; ++j) rb[j] = *(const u32x4*)(Bp + (size_t)j * RSTEP * g.ldb + (kt + 2) * BK);
;         }
;       }
;       bf16x8 af[NKK][MF], bfr[NKK][2];
; #pragma unroll
;       for (int kk = 0; kk < NKK; ++kk) {
; #pragma unroll
;         for (int ni = 0; ni < 2; ++ni) bfr[kk][ni] = *(const bf16x8*)(sB + (wn * 64 + ni * 32 + l31) * LS + kk * 16 + h * 8);
; #pragma unroll
;         for (int mi = 0; mi < MF; ++mi) af[kk][mi] = *(const bf16x8*)(sA + (wm * (MF * 32) + mi * 32 + l31) * LS + kk * 16 + h * 8);
;       }
;       __builtin_amdgcn_sched_barrier(0);
; #pragma unroll
;       for (int kk = 0; kk < NKK; ++kk)
; #pragma unroll
;         for (int mi = 0; mi < MF; ++mi)
; #pragma unroll
;           for (int ni = 0; ni < 2; ++ni) acc[mi][ni] = MFMA32(bfr[kk][ni], af[kk][mi], acc[mi][ni]);
.Ldma_dn_loop:
	s_waitcnt vmcnt(0)
	s_waitcnt lgkmcnt(0)
	s_barrier
	s_add_i32 m0, s100, 0x0
	s_nop 0
	global_load_lds_dwordx4 v108, s[12:13]
	s_add_i32 m0, s100, 0x1000
	s_nop 0
	global_load_lds_dwordx4 v109, s[12:13]
	s_add_i32 m0, s100, 0x2000
	s_nop 0
	global_load_lds_dwordx4 v110, s[12:13]
	s_add_i32 m0, s100, 0x3000
	s_nop 0
	global_load_lds_dwordx4 v111, s[12:13]
	s_add_i32 m0, s100, 0x4000
	s_nop 0
	global_load_lds_dwordx4 v108, s[14:15]
	s_add_i32 m0, s100, 0x5000
	s_nop 0
	global_load_lds_dwordx4 v109, s[14:15]
	s_add_i32 m0, s100, 0x6000
	s_nop 0
	global_load_lds_dwordx4 v110, s[14:15]
	s_add_i32 m0, s100, 0x7000
	s_nop 0
	global_load_lds_dwordx4 v111, s[14:15]
	s_add_u32 s12, s12, 0x80
	s_addc_u32 s13, s13, 0
	s_add_u32 s14, s14, 0x80
	s_addc_u32 s15, s15, 0
	ds_read_b128 v[150:153], v234 offset:32768
	ds_read_b128 v[154:157], v234 offset:36864
	ds_read_b128 v[158:161], v114 offset:32768
	ds_read_b128 v[162:165], v114 offset:36864
	ds_read_b128 v[168:171], v235 offset:32768
	ds_read_b128 v[172:175], v235 offset:36864
	ds_read_b128 v[176:179], v115 offset:32768
	ds_read_b128 v[180:183], v115 offset:36864
	ds_read_b128 v[184:187], v236 offset:32768
	ds_read_b128 v[188:191], v236 offset:36864
	ds_read_b128 v[192:195], v116 offset:32768
	ds_read_b128 v[198:201], v116 offset:36864
	ds_read_b128 v[218:221], v237 offset:32768
	ds_read_b128 v[222:225], v237 offset:36864
	ds_read_b128 v[226:229], v117 offset:32768
	ds_read_b128 v[230:233], v117 offset:36864
	v_mfma_f32_32x32x16_bf16 v[52:67], v[68:71], v[76:79], v[52:67]
	v_mfma_f32_32x32x16_bf16 v[36:51], v[72:75], v[76:79], v[36:51]
	v_mfma_f32_32x32x16_bf16 v[20:35], v[68:71], v[80:83], v[20:35]
	v_mfma_f32_32x32x16_bf16 v[4:19], v[72:75], v[80:83], v[4:19]
	v_mfma_f32_32x32x16_bf16 v[52:67], v[84:87], v[92:95], v[52:67]
	v_mfma_f32_32x32x16_bf16 v[36:51], v[88:91], v[92:95], v[36:51]
	v_mfma_f32_32x32x16_bf16 v[20:35], v[84:87], v[96:99], v[20:35]
	v_mfma_f32_32x32x16_bf16 v[4:19], v[88:91], v[96:99], v[4:19]
	v_mfma_f32_32x32x16_bf16 v[52:67], v[118:121], v[126:129], v[52:67]
	v_mfma_f32_32x32x16_bf16 v[36:51], v[122:125], v[126:129], v[36:51]
	v_mfma_f32_32x32x16_bf16 v[20:35], v[118:121], v[130:133], v[20:35]
	v_mfma_f32_32x32x16_bf16 v[4:19], v[122:125], v[130:133], v[4:19]
	v_mfma_f32_32x32x16_bf16 v[52:67], v[134:137], v[142:145], v[52:67]
	v_mfma_f32_32x32x16_bf16 v[36:51], v[138:141], v[142:145], v[36:51]
	v_mfma_f32_32x32x16_bf16 v[20:35], v[134:137], v[146:149], v[20:35]
	v_mfma_f32_32x32x16_bf16 v[4:19], v[138:141], v[146:149], v[4:19]
	s_waitcnt vmcnt(0)
	s_waitcnt lgkmcnt(0)
	s_barrier
	s_add_i32 m0, s100, 0x8000
	s_nop 0
	global_load_lds_dwordx4 v108, s[12:13]
	s_add_i32 m0, s100, 0x9000
	s_nop 0
	global_load_lds_dwordx4 v109, s[12:13]
	s_add_i32 m0, s100, 0xa000
	s_nop 0
	global_load_lds_dwordx4 v110, s[12:13]
	s_add_i32 m0, s100, 0xb000
	s_nop 0
	global_load_lds_dwordx4 v111, s[12:13]
	s_add_i32 m0, s100, 0xc000
	s_nop 0
	global_load_lds_dwordx4 v108, s[14:15]
	s_add_i32 m0, s100, 0xd000
	s_nop 0
	global_load_lds_dwordx4 v109, s[14:15]
	s_add_i32 m0, s100, 0xe000
	s_nop 0
	global_load_lds_dwordx4 v110, s[14:15]
	s_add_i32 m0, s100, 0xf000
	s_nop 0
	global_load_lds_dwordx4 v111, s[14:15]
	s_add_u32 s12, s12, 0x80
	s_addc_u32 s13, s13, 0
	s_add_u32 s14, s14, 0x80
	s_addc_u32 s15, s15, 0
	ds_read_b128 v[68:71], v234
	ds_read_b128 v[72:75], v234 offset:4096
	ds_read_b128 v[76:79], v114
	ds_read_b128 v[80:83], v114 offset:4096
	ds_read_b128 v[84:87], v235
	ds_read_b128 v[88:91], v235 offset:4096
	ds_read_b128 v[92:95], v115
	ds_read_b128 v[96:99], v115 offset:4096
	ds_read_b128 v[118:121], v236
	ds_read_b128 v[122:125], v236 offset:4096
	ds_read_b128 v[126:129], v116
	ds_read_b128 v[130:133], v116 offset:4096
	ds_read_b128 v[134:137], v237
	ds_read_b128 v[138:141], v237 offset:4096
	ds_read_b128 v[142:145], v117
	ds_read_b128 v[146:149], v117 offset:4096
	v_mfma_f32_32x32x16_bf16 v[52:67], v[150:153], v[158:161], v[52:67]
	v_mfma_f32_32x32x16_bf16 v[36:51], v[154:157], v[158:161], v[36:51]
	v_mfma_f32_32x32x16_bf16 v[20:35], v[150:153], v[162:165], v[20:35]
	v_mfma_f32_32x32x16_bf16 v[4:19], v[154:157], v[162:165], v[4:19]
	v_mfma_f32_32x32x16_bf16 v[52:67], v[168:171], v[176:179], v[52:67]
	v_mfma_f32_32x32x16_bf16 v[36:51], v[172:175], v[176:179], v[36:51]
	v_mfma_f32_32x32x16_bf16 v[20:35], v[168:171], v[180:183], v[20:35]
	v_mfma_f32_32x32x16_bf16 v[4:19], v[172:175], v[180:183], v[4:19]
	v_mfma_f32_32x32x16_bf16 v[52:67], v[184:187], v[192:195], v[52:67]
	v_mfma_f32_32x32x16_bf16 v[36:51], v[188:191], v[192:195], v[36:51]
	v_mfma_f32_32x32x16_bf16 v[20:35], v[184:187], v[198:201], v[20:35]
	v_mfma_f32_32x32x16_bf16 v[4:19], v[188:191], v[198:201], v[4:19]
	v_mfma_f32_32x32x16_bf16 v[52:67], v[218:221], v[226:229], v[52:67]
	v_mfma_f32_32x32x16_bf16 v[36:51], v[222:225], v[226:229], v[36:51]
	v_mfma_f32_32x32x16_bf16 v[20:35], v[218:221], v[230:233], v[20:35]
	v_mfma_f32_32x32x16_bf16 v[4:19], v[222:225], v[230:233], v[4:19]
	s_add_i32 s9, s9, -1
	s_cmp_lg_u32 s9, 0
	s_cbranch_scc1 .Ldma_dn_loop
	s_waitcnt vmcnt(0)
	s_waitcnt lgkmcnt(0)
	s_barrier
; template <int MF, int BK, class Epi>
; DI void gemm_phase_t(char* lds, const GemmDesc g, const Epi epi) {
;     ...
;     for (int kt = 0; kt < nk; ++kt) {
;       __syncthreads();
;       const u16* sA = sbase + (kt & 1) * STG;
;       const u16* sB = sA + BM * LS;
;       if (kt + 1 < nk) {
;         u16* nA = sbase + ((kt + 1) & 1) * STG;
; #pragma unroll
;         for (int j = 0; j < APT; ++j) *(u32x4*)(nA + (lr + RSTEP * j) * LS + lc * 8) = ra[j];
; #pragma unroll
;         for (int j = 0; j < BPT; ++j) *(u32x4*)(nA + BM * LS + (lr + RSTEP * j) * LS + lc * 8) = rb[j];
;         if (kt + 2 < nk) {
; #pragma unroll
;           for (int j = 0; j < APT; ++j) ra[j] = *(const u32x4*)(Ap + (size_t)j * RSTEP * g.lda + (kt + 2) * BK);
; #pragma unroll
;           for (int j = 0; j < BPT; ++j) rb[j] = *(const u32x4*)(Bp + (size_t)j * RSTEP * g.ldb + (kt + 2) * BK);
;         }
;       }
;       bf16x8 af[NKK][MF], bfr[NKK][2];
; #pragma unroll
;       for (int kk = 0; kk < NKK; ++kk) {
; #pragma unroll
;         for (int ni = 0; ni < 2; ++ni) bfr[kk][ni] = *(const bf16x8*)(sB + (wn * 64 + ni * 32 + l31) * LS + kk * 16 + h * 8);
; #pragma unroll
;         for (int mi = 0; mi < MF; ++mi) af[kk][mi] = *(const bf16x8*)(sA + (wm * (MF * 32) + mi * 32 + l31) * LS + kk * 16 + h * 8);
;       }
;       __builtin_amdgcn_sched_barrier(0);
; #pragma unroll
;       for (int kk = 0; kk < NKK; ++kk)
; #pragma unroll
;         for (int mi = 0; mi < MF; ++mi)
; #pragma unroll
;           for (int ni = 0; ni < 2; ++ni) acc[mi][ni] = MFMA32(bfr[kk][ni], af[kk][mi], acc[mi][ni]);
;   template <int MF> DI void operator()(f32x16 (&acc)[MF][2], int mb, int nb, int l31, int h) const {
; #pragma unroll
;     for (int mi = 0; mi < MF; ++mi) {
;       const int row = mb + mi * 32 + l31;
;       const float* gr = gate + (size_t)modrow(row) * 6144;
;       const float* rp = row < TL ? res_lat + (size_t)row * D : res_ctx + (size_t)(row - TL) * D;
;       float* op = row < TL ? out_lat + (size_t)row * D : out_ctx + (size_t)(row - TL) * D;
; #pragma unroll
;       for (int g4 = 0; g4 < 4; ++g4)
; #pragma unroll
;         for (int ni = 0; ni < 2; ++ni) {
;           const int col0 = nb + 16 * g4 + 8 * h + 4 * ni;
;           const float4 gt = *(const float4*)(gr + col0);
;           const float4 rv = *(const float4*)(rp + col0);
	ds_read_b128 v[150:153], v234 offset:32768
	ds_read_b128 v[154:157], v234 offset:36864
	ds_read_b128 v[158:161], v114 offset:32768
	ds_read_b128 v[162:165], v114 offset:36864
	ds_read_b128 v[168:171], v235 offset:32768
	ds_read_b128 v[172:175], v235 offset:36864
	ds_read_b128 v[176:179], v115 offset:32768
	ds_read_b128 v[180:183], v115 offset:36864
	ds_read_b128 v[184:187], v236 offset:32768
	ds_read_b128 v[188:191], v236 offset:36864
	ds_read_b128 v[192:195], v116 offset:32768
	ds_read_b128 v[198:201], v116 offset:36864
	ds_read_b128 v[218:221], v237 offset:32768
	ds_read_b128 v[222:225], v237 offset:36864
	ds_read_b128 v[226:229], v117 offset:32768
	ds_read_b128 v[230:233], v117 offset:36864
	v_mfma_f32_32x32x16_bf16 v[52:67], v[68:71], v[76:79], v[52:67]
	v_mfma_f32_32x32x16_bf16 v[36:51], v[72:75], v[76:79], v[36:51]
	v_mfma_f32_32x32x16_bf16 v[20:35], v[68:71], v[80:83], v[20:35]
	v_mfma_f32_32x32x16_bf16 v[4:19], v[72:75], v[80:83], v[4:19]
	v_mfma_f32_32x32x16_bf16 v[52:67], v[84:87], v[92:95], v[52:67]
	v_mfma_f32_32x32x16_bf16 v[36:51], v[88:91], v[92:95], v[36:51]
	v_mfma_f32_32x32x16_bf16 v[20:35], v[84:87], v[96:99], v[20:35]
	v_mfma_f32_32x32x16_bf16 v[4:19], v[88:91], v[96:99], v[4:19]
	v_mfma_f32_32x32x16_bf16 v[52:67], v[118:121], v[126:129], v[52:67]
	v_mfma_f32_32x32x16_bf16 v[36:51], v[122:125], v[126:129], v[36:51]
	v_mfma_f32_32x32x16_bf16 v[20:35], v[118:121], v[130:133], v[20:35]
	v_mfma_f32_32x32x16_bf16 v[4:19], v[122:125], v[130:133], v[4:19]
	v_mfma_f32_32x32x16_bf16 v[52:67], v[134:137], v[142:145], v[52:67]
	v_mfma_f32_32x32x16_bf16 v[36:51], v[138:141], v[142:145], v[36:51]
	v_mfma_f32_32x32x16_bf16 v[20:35], v[134:137], v[146:149], v[20:35]
	v_mfma_f32_32x32x16_bf16 v[4:19], v[138:141], v[146:149], v[4:19]
	s_waitcnt lgkmcnt(0)
	v_mfma_f32_32x32x16_bf16 v[52:67], v[150:153], v[158:161], v[52:67]
	v_mfma_f32_32x32x16_bf16 v[36:51], v[154:157], v[158:161], v[36:51]
	v_mfma_f32_32x32x16_bf16 v[20:35], v[150:153], v[162:165], v[20:35]
	v_mfma_f32_32x32x16_bf16 v[4:19], v[154:157], v[162:165], v[4:19]
	v_mfma_f32_32x32x16_bf16 v[52:67], v[168:171], v[176:179], v[52:67]
	v_mfma_f32_32x32x16_bf16 v[36:51], v[172:175], v[176:179], v[36:51]
	v_mfma_f32_32x32x16_bf16 v[20:35], v[168:171], v[180:183], v[20:35]
	v_mfma_f32_32x32x16_bf16 v[4:19], v[172:175], v[180:183], v[4:19]
	v_mfma_f32_32x32x16_bf16 v[52:67], v[184:187], v[192:195], v[52:67]
	v_mfma_f32_32x32x16_bf16 v[36:51], v[188:191], v[192:195], v[36:51]
	v_mfma_f32_32x32x16_bf16 v[20:35], v[184:187], v[198:201], v[20:35]
	v_mfma_f32_32x32x16_bf16 v[4:19], v[188:191], v[198:201], v[4:19]
	v_mfma_f32_32x32x16_bf16 v[52:67], v[218:221], v[226:229], v[52:67]
	v_mfma_f32_32x32x16_bf16 v[36:51], v[222:225], v[226:229], v[36:51]
	v_mfma_f32_32x32x16_bf16 v[20:35], v[218:221], v[230:233], v[20:35]
	v_mfma_f32_32x32x16_bf16 v[4:19], v[222:225], v[230:233], v[4:19]
	v_or_b32_e32 v68, s8, v113
	v_readlane_b32 s8, v252, 40
	s_add_i32 s6, s6, s8
	s_cmpk_gt_i32 s6, 0x7ff
	v_readlane_b32 s9, v252, 41
	v_mov_b32_e32 v88, s21
	v_mov_b32_e32 v89, s22
	v_mov_b32_e32 v90, s20
	v_add_u32_e32 v86, s7, v112
	v_min_i32_e32 v69, 0x8000, v86
	v_ashrrev_i32_e32 v69, 12, v69
	s_mov_b32 s7, 0x8000
	v_mul_hi_i32_i24_e32 v71, 0x6000, v69
	v_mul_i32_i24_e32 v70, 0x6000, v69
	v_cmp_gt_i32_e32 vcc, s7, v86
	v_add_u32_e32 v69, 0xffff8000, v86
	v_ashrrev_i32_e32 v72, 31, v86
	v_cndmask_b32_e32 v73, 0, v72, vcc
	v_cndmask_b32_e32 v72, v69, v86, vcc
	v_mov_b32_e32 v87, s23
	v_ashrrev_i32_e32 v69, 31, v68
	v_lshl_add_u64 v[70:71], s[2:3], 0, v[70:71]
	v_cndmask_b32_e32 v75, v87, v88, vcc
	v_cndmask_b32_e32 v74, v89, v90, vcc
	v_lshlrev_b64 v[72:73], 12, v[72:73]
	v_lshlrev_b64 v[68:69], 2, v[68:69]
	v_lshl_add_u64 v[72:73], v[74:75], 0, v[72:73]
	v_lshl_add_u64 v[84:85], v[72:73], 0, v[68:69]
	s_movk_i32 s7, 0x7fe0
	v_cmp_gt_i32_e32 vcc, s7, v86
	v_lshl_add_u64 v[82:83], v[70:71], 0, v[68:69]
	s_movk_i32 s7, 0x7fe0
	v_cmp_gt_i32_e32 vcc, s7, v86
	v_or_b32_e32 v76, 32, v86
	v_ashrrev_i32_e32 v72, 31, v76
	v_add_u32_e32 v74, 0xffff8020, v86
	v_cndmask_b32_e32 v73, 0, v72, vcc
	v_cndmask_b32_e32 v72, v74, v76, vcc
	v_cndmask_b32_e32 v75, v87, v88, vcc
	v_cndmask_b32_e32 v74, v89, v90, vcc
	v_lshlrev_b64 v[72:73], 12, v[72:73]
	v_lshl_add_u64 v[72:73], v[74:75], 0, v[72:73]
	v_lshl_add_u64 v[80:81], v[72:73], 0, v[68:69]
	global_load_dwordx4 v[118:121], v[82:83], off
	global_load_dwordx4 v[150:153], v[84:85], off
	global_load_dwordx4 v[122:125], v[82:83], off offset:16
	global_load_dwordx4 v[154:157], v[84:85], off offset:16
	global_load_dwordx4 v[126:129], v[82:83], off offset:64
	global_load_dwordx4 v[158:161], v[84:85], off offset:64
	global_load_dwordx4 v[130:133], v[82:83], off offset:80
	global_load_dwordx4 v[162:165], v[84:85], off offset:80
	global_load_dwordx4 v[134:137], v[82:83], off offset:128
	global_load_dwordx4 v[168:171], v[84:85], off offset:128
	global_load_dwordx4 v[138:141], v[82:83], off offset:144
	global_load_dwordx4 v[172:175], v[84:85], off offset:144
	global_load_dwordx4 v[142:145], v[82:83], off offset:192
	global_load_dwordx4 v[176:179], v[84:85], off offset:192
	global_load_dwordx4 v[146:149], v[82:83], off offset:208
	global_load_dwordx4 v[180:183], v[84:85], off offset:208
	global_load_dwordx4 v[184:187], v[80:81], off
	global_load_dwordx4 v[188:191], v[80:81], off offset:16
	global_load_dwordx4 v[192:195], v[80:81], off offset:64
	global_load_dwordx4 v[198:201], v[80:81], off offset:80
	global_load_dwordx4 v[218:221], v[80:81], off offset:128
	global_load_dwordx4 v[222:225], v[80:81], off offset:144
	global_load_dwordx4 v[226:229], v[80:81], off offset:192
	global_load_dwordx4 v[230:233], v[80:81], off offset:208
	s_waitcnt vmcnt(8)
;   template <int MF> DI void operator()(f32x16 (&acc)[MF][2], int mb, int nb, int l31, int h) const {
;     ...
; #pragma unroll
;       for (int g4 = 0; g4 < 4; ++g4)
; #pragma unroll
;         for (int ni = 0; ni < 2; ++ni) {
;           const int col0 = nb + 16 * g4 + 8 * h + 4 * ni;
;           const float4 gt = *(const float4*)(gr + col0);
;           const float4 rv = *(const float4*)(rp + col0);
;           *(float4*)(op + col0) = make_float4(rv.x + gt.x * acc[mi][ni][4 * g4], rv.y + gt.y * acc[mi][ni][4 * g4 + 1], rv.z + gt.z * acc[mi][ni][4 * g4 + 2], rv.w + gt.w * acc[mi][ni][4 * g4 + 3]);
;         }
;     }
	s_nop 4
	v_fma_f32 v52, v52, v118, v150
	v_fma_f32 v53, v53, v119, v151
	v_fma_f32 v54, v54, v120, v152
	v_fma_f32 v55, v55, v121, v153
	global_store_dwordx4 v[84:85], v[52:55], off
	v_fma_f32 v36, v36, v122, v154
	v_fma_f32 v37, v37, v123, v155
	v_fma_f32 v38, v38, v124, v156
	v_fma_f32 v39, v39, v125, v157
	global_store_dwordx4 v[84:85], v[36:39], off offset:16
	v_fma_f32 v56, v56, v126, v158
	v_fma_f32 v57, v57, v127, v159
	v_fma_f32 v58, v58, v128, v160
	v_fma_f32 v59, v59, v129, v161
	global_store_dwordx4 v[84:85], v[56:59], off offset:64
	v_fma_f32 v40, v40, v130, v162
	v_fma_f32 v41, v41, v131, v163
	v_fma_f32 v42, v42, v132, v164
	v_fma_f32 v43, v43, v133, v165
	global_store_dwordx4 v[84:85], v[40:43], off offset:80
	v_fma_f32 v60, v60, v134, v168
	v_fma_f32 v61, v61, v135, v169
	v_fma_f32 v62, v62, v136, v170
	v_fma_f32 v63, v63, v137, v171
	global_store_dwordx4 v[84:85], v[60:63], off offset:128
	v_fma_f32 v44, v44, v138, v172
	v_fma_f32 v45, v45, v139, v173
	v_fma_f32 v46, v46, v140, v174
	v_fma_f32 v47, v47, v141, v175
	global_store_dwordx4 v[84:85], v[44:47], off offset:144
	v_fma_f32 v64, v64, v142, v176
	v_fma_f32 v65, v65, v143, v177
	v_fma_f32 v66, v66, v144, v178
	v_fma_f32 v67, v67, v145, v179
	global_store_dwordx4 v[84:85], v[64:67], off offset:192
	v_fma_f32 v48, v48, v146, v180
	v_fma_f32 v49, v49, v147, v181
	v_fma_f32 v50, v50, v148, v182
	v_fma_f32 v51, v51, v149, v183
	global_store_dwordx4 v[84:85], v[48:51], off offset:208
	s_waitcnt vmcnt(8)
	v_fma_f32 v20, v20, v118, v184
	v_fma_f32 v21, v21, v119, v185
	v_fma_f32 v22, v22, v120, v186
	v_fma_f32 v23, v23, v121, v187
	global_store_dwordx4 v[80:81], v[20:23], off
	v_fma_f32 v4, v4, v122, v188
	v_fma_f32 v5, v5, v123, v189
	v_fma_f32 v6, v6, v124, v190
	v_fma_f32 v7, v7, v125, v191
	global_store_dwordx4 v[80:81], v[4:7], off offset:16
	v_fma_f32 v24, v24, v126, v192
	v_fma_f32 v25, v25, v127, v193
	v_fma_f32 v26, v26, v128, v194
	v_fma_f32 v27, v27, v129, v195
	global_store_dwordx4 v[80:81], v[24:27], off offset:64
	v_fma_f32 v8, v8, v130, v198
	v_fma_f32 v9, v9, v131, v199
	v_fma_f32 v10, v10, v132, v200
	v_fma_f32 v11, v11, v133, v201
	global_store_dwordx4 v[80:81], v[8:11], off offset:80
	v_fma_f32 v28, v28, v134, v218
	v_fma_f32 v29, v29, v135, v219
	v_fma_f32 v30, v30, v136, v220
	v_fma_f32 v31, v31, v137, v221
	global_store_dwordx4 v[80:81], v[28:31], off offset:128
	v_fma_f32 v12, v12, v138, v222
	v_fma_f32 v13, v13, v139, v223
	v_fma_f32 v14, v14, v140, v224
	v_fma_f32 v15, v15, v141, v225
	global_store_dwordx4 v[80:81], v[12:15], off offset:144
	v_fma_f32 v32, v32, v142, v226
	v_fma_f32 v33, v33, v143, v227
	v_fma_f32 v34, v34, v144, v228
	v_fma_f32 v35, v35, v145, v229
	global_store_dwordx4 v[80:81], v[32:35], off offset:192
	v_fma_f32 v16, v16, v146, v230
	v_fma_f32 v17, v17, v147, v231
	v_fma_f32 v18, v18, v148, v232
	v_fma_f32 v19, v19, v149, v233
	global_store_dwordx4 v[80:81], v[16:19], off offset:208
	s_cbranch_scc0 .LBB0_34

; __device__ __forceinline__ size_t wofs(int layer) { return (layer & 1) ? W2_DELTA : (size_t)0; }
; DI int tid_l() { int t = threadIdx.x; asm volatile("" : "+v"(t)); return t; }
; DI int bid_l() { int t = blockIdx.x; asm volatile("" : "+s"(t)); return t; }
; template <int MF, int BK, class Epi>
; DI void gemm_phase_t(char* lds, const GemmDesc g, const Epi epi) {
;   constexpr int BM = MF * 64, LS = BK + 8, CPR = BK / 8, RSTEP = 256 / CPR;
;   constexpr int APT = BM * CPR / 256, BPT = 128 * CPR / 256, STG = (BM + 128) * LS, NKK = BK / 16;
;   u16* sbase = (u16*)lds;
;   const int tid = tid_l(), lane = tid & 63, w = tid >> 6, wm = w >> 1, wn = w & 1, l31 = lane & 31, h = lane >> 5;
;   const int ntn = g.Npad / 128, ntm = g.M / BM, ntiles = ntm * ntn, nk = g.K / BK;
;   const int lr = tid / CPR, lc = tid % CPR;
;   for (int t = bid_l(); t < ntiles; t += gridDim.x) {
;     const int tn = t % ntn, tm = t / ntn;
;     const int m0 = tm * BM, n0 = tn * 128;
;     const u16* Ap = g.A + (size_t)(m0 + lr) * g.lda + lc * 8;
;     const u16* Bp = g.Bt + (size_t)(n0 + lr) * g.ldb + lc * 8;
; DI void run_phase(const Params& p, char* lds, int ph) {
;     ...
;       else { if (en(3)) { GemmDesc g{(const u16*)(ws + OFF_HN), 1024, (const u16*)(ws + wofs(layer) + OFF_WIN), 1024, TA, 2048, 1024};
;         gemm_phase(lds, g, EpiOddIn{(u16*)(ws + OFF_ZO), (u16*)(ws + OFF_QA), (u16*)(ws + OFF_QAC), (u16*)(ws + OFF_KA), (const float*)(ws + OFF_ROPE)}); } }
.LBB0_904:
	s_cmp_gt_i32 s40, 0
	s_mov_b64 s[2:3], -1
	s_cbranch_scc0 .LBB0_368
	v_readlane_b32 s2, v253, 33
	v_readlane_b32 s3, v253, 34
	s_mov_b64 s[0:1], -1
	s_and_b64 vcc, exec, s[2:3]
	s_cbranch_vccz .LBB0_950
	v_mov_b32_e32 v2, v0
	v_readlane_b32 s18, v251, 0
	s_cmpk_gt_i32 s18, 0x10ff
	s_cbranch_scc1 .LBB0_949
	v_ashrrev_i32_e32 v4, 31, v2
	v_lshrrev_b32_e32 v4, 29, v4
	v_add_u32_e32 v4, v2, v4
	v_ashrrev_i32_e32 v94, 3, v4
	v_and_b32_e32 v4, -8, v4
	v_sub_u32_e32 v6, v2, v4
	v_lshlrev_b32_e32 v4, 3, v6
	s_add_u32 s4, s30, 0x147ac000
	v_ashrrev_i32_e32 v5, 31, v4
	s_addc_u32 s5, s31, 0
	v_lshlrev_b64 v[4:5], 1, v[4:5]
	v_lshl_add_u64 v[72:73], s[4:5], 0, v[4:5]
	v_lshl_add_u64 v[4:5], s[30:31], 0, v[4:5]
	s_mov_b64 s[0:1], 0x1cfb0000
	s_add_u32 s6, s30, 0x37ac000
	v_and_b32_e32 v77, 31, v2
	v_bfe_u32 v7, v2, 5, 1
	v_lshl_add_u64 v[74:75], v[4:5], 0, s[0:1]
	v_lshlrev_b32_e32 v5, 4, v6
	v_and_b32_e32 v95, 64, v2
	v_and_b32_e32 v8, 0x5f, v2
	v_ashrrev_i32_e32 v6, 1, v2
	v_lshrrev_b32_e32 v2, 4, v2
	s_addc_u32 s7, s31, 0
	v_and_b32_e32 v96, 0xffffffc0, v6
	v_and_b32_e32 v97, 4, v2
	v_lshlrev_b32_e32 v2, 5, v7
	s_add_u32 s8, s30, 0x105cc000
	v_lshlrev_b32_e32 v4, 4, v7
	v_or_b32_e32 v9, v96, v77
	v_lshlrev_b32_e32 v76, 3, v7
	v_lshl_add_u64 v[6:7], s[30:31], 0, v[2:3]
	s_mov_b64 s[0:1], 0x1fb10000
	s_movk_i32 s2, 0x90
	s_addc_u32 s9, s31, 0
	v_lshl_add_u64 v[78:79], v[6:7], 0, s[0:1]
	v_mul_lo_u32 v2, v94, s2
	v_mad_u64_u32 v[80:81], s[0:1], v9, s2, v[4:5]
	s_add_u32 s10, s30, 0x125cc000
	v_add_u32_e32 v98, v5, v2
	v_add_u32_e32 v2, 0x3600, v2
	v_readlane_b32 s0, v252, 40
	s_addc_u32 s11, s31, 0
	v_mad_u32_u24 v81, v8, s2, v4
	s_lshl_b32 s19, s18, 7
	s_lshl_b32 s20, s0, 7
	v_or_b32_e32 v99, v95, v76
	v_add_u32_e32 v100, v5, v2
	v_readlane_b32 s1, v252, 41
	v_bfe_u32 v4, v0, 1, 3
	v_bfe_u32 v5, v0, 5, 1
	v_xor_b32_e32 v4, v4, v5
	v_lshlrev_b32_e32 v4, 4, v4
	v_add_u32_e32 v4, 0x100, v4
	v_and_b32_e32 v5, 31, v0
	v_bfe_u32 v6, v0, 7, 1
	v_lshl_or_b32 v6, v6, 6, v5
	v_lshl_add_u32 v80, v6, 7, v4
	v_bfe_u32 v6, v0, 6, 1
	v_lshl_or_b32 v6, v6, 6, v5
	v_lshl_add_u32 v238, v6, 7, v4
	v_add_u32_e32 v238, 0x4000, v238
	v_xor_b32_e32 v81, 0x20, v80
	v_xor_b32_e32 v239, 0x20, v238
	v_xor_b32_e32 v98, 0x40, v80
	v_xor_b32_e32 v240, 0x40, v238
	v_xor_b32_e32 v100, 0x60, v80
	v_xor_b32_e32 v241, 0x60, v238
	s_branch .LBB0_910

; DI int bid_l() { int t = blockIdx.x; asm volatile("" : "+s"(t)); return t; }
; DI f32x16 zero16() { f32x16 z; for (int i = 0; i < 16; ++i) z[i] = 0.f; return z; }
; template <int MF, int BK, class Epi>
; DI void gemm_phase_t(char* lds, const GemmDesc g, const Epi epi) {
;     ...
;   for (int t = bid_l(); t < ntiles; t += gridDim.x) {
;     const int tn = t % ntn, tm = t / ntn;
;     const int m0 = tm * BM, n0 = tn * 128;
;     const u16* Ap = g.A + (size_t)(m0 + lr) * g.lda + lc * 8;
;     const u16* Bp = g.Bt + (size_t)(n0 + lr) * g.ldb + lc * 8;
;     u32x4 ra[APT], rb[BPT];
; #pragma unroll
;     for (int j = 0; j < APT; ++j) ra[j] = *(const u32x4*)(Ap + (size_t)j * RSTEP * g.lda);
; #pragma unroll
;     for (int j = 0; j < BPT; ++j) rb[j] = *(const u32x4*)(Bp + (size_t)j * RSTEP * g.ldb);
; #pragma unroll
;     for (int j = 0; j < APT; ++j) *(u32x4*)(sbase + (lr + RSTEP * j) * LS + lc * 8) = ra[j];
; #pragma unroll
;     for (int j = 0; j < BPT; ++j) *(u32x4*)(sbase + BM * LS + (lr + RSTEP * j) * LS + lc * 8) = rb[j];
;     if (nk > 1) {
; #pragma unroll
;       for (int j = 0; j < APT; ++j) ra[j] = *(const u32x4*)(Ap + (size_t)j * RSTEP * g.lda + BK);
; #pragma unroll
;       for (int j = 0; j < BPT; ++j) rb[j] = *(const u32x4*)(Bp + (size_t)j * RSTEP * g.ldb + BK);
;     }
;     f32x16 acc[MF][2];
; #pragma unroll
;     for (int i = 0; i < MF; ++i)
; #pragma unroll
;       for (int j = 0; j < 2; ++j) acc[i][j] = zero16();
.LBB0_910:
	s_ashr_i32 s0, s18, 31
	s_lshr_b32 s0, s0, 28
	s_add_i32 s0, s18, s0
	s_ashr_i32 s1, s0, 4
	s_lshl_b32 s0, s1, 7
	v_add_u32_e32 v4, s0, v94
	v_ashrrev_i32_e32 v5, 31, v4
	v_lshlrev_b64 v[4:5], 11, v[4:5]
	v_lshl_add_u64 v[4:5], v[72:73], 0, v[4:5]
	s_lshl_b32 s22, s1, 11
	s_sub_i32 s21, s19, s22
	s_mov_b32 s1, 0x20000
	v_add_u32_e32 v20, s21, v94
	v_ashrrev_i32_e32 v21, 31, v20
	v_lshlrev_b64 v[20:21], 11, v[20:21]
	v_lshl_add_u64 v[20:21], v[74:75], 0, v[20:21]
	s_waitcnt lgkmcnt(0)
	v_mov_b32_e32 v60, 0
	v_readfirstlane_b32 s98, v4
	v_readfirstlane_b32 s99, v5
	v_readfirstlane_b32 s100, v20
	v_readfirstlane_b32 s101, v21
	v_bfe_u32 v62, v0, 4, 3
	v_and_b32_e32 v63, 7, v0
	v_xor_b32_e32 v62, v62, v63
	v_lshlrev_b32_e32 v62, 4, v62
	v_bfe_u32 v63, v0, 3, 3
	s_movk_i32 s2, 0x800
	v_mad_u32_u24 v68, v63, s2, v62
	v_add_u32_e32 v69, 0x10000, v68
	v_add_u32_e32 v70, 0x20000, v68
	v_add_u32_e32 v71, 0x30000, v68
	v_lshrrev_b32_e32 v61, 6, v0
	v_lshlrev_b32_e32 v61, 10, v61
	v_add_u32_e32 v61, 0x100, v61
	s_nop 0
	v_readfirstlane_b32 s3, v61
	v_mov_b32_e32 v4, 0
	v_mov_b32_e32 v5, 0
	v_mov_b32_e32 v6, 0
	v_mov_b32_e32 v7, 0
	v_mov_b32_e32 v8, 0
	v_mov_b32_e32 v9, 0
	v_mov_b32_e32 v10, 0
	v_mov_b32_e32 v11, 0
	v_mov_b32_e32 v12, 0
	v_mov_b32_e32 v13, 0
	v_mov_b32_e32 v14, 0
	v_mov_b32_e32 v15, 0
	v_mov_b32_e32 v16, 0
	v_mov_b32_e32 v17, 0
	v_mov_b32_e32 v18, 0
	v_mov_b32_e32 v19, 0
	v_mov_b32_e32 v20, 0
	v_mov_b32_e32 v21, 0
	v_mov_b32_e32 v22, 0
	v_mov_b32_e32 v23, 0
	v_mov_b32_e32 v24, 0
	v_mov_b32_e32 v25, 0
	v_mov_b32_e32 v26, 0
	v_mov_b32_e32 v27, 0
	v_mov_b32_e32 v28, 0
	v_mov_b32_e32 v29, 0
	v_mov_b32_e32 v30, 0
	v_mov_b32_e32 v31, 0
	v_mov_b32_e32 v32, 0
	v_mov_b32_e32 v33, 0
	v_mov_b32_e32 v34, 0
	v_mov_b32_e32 v35, 0
	v_mov_b32_e32 v36, 0
	v_mov_b32_e32 v37, 0
	v_mov_b32_e32 v38, 0
	v_mov_b32_e32 v39, 0
	v_mov_b32_e32 v40, 0
	v_mov_b32_e32 v41, 0
	v_mov_b32_e32 v42, 0
	v_mov_b32_e32 v43, 0
	v_mov_b32_e32 v44, 0
	v_mov_b32_e32 v45, 0
	v_mov_b32_e32 v46, 0
	v_mov_b32_e32 v47, 0
	v_mov_b32_e32 v48, 0
	v_mov_b32_e32 v49, 0
	v_mov_b32_e32 v50, 0
	v_mov_b32_e32 v51, 0
	v_mov_b32_e32 v52, 0
	v_mov_b32_e32 v53, 0
	v_mov_b32_e32 v54, 0
	v_mov_b32_e32 v55, 0
	v_mov_b32_e32 v56, 0
	v_mov_b32_e32 v57, 0
	v_mov_b32_e32 v58, 0
	v_mov_b32_e32 v59, 0
	v_mov_b32_e32 v60, 0
	v_mov_b32_e32 v61, 0
	v_mov_b32_e32 v62, 0
	v_mov_b32_e32 v63, 0
	v_mov_b32_e32 v64, 0
	v_mov_b32_e32 v65, 0
	v_mov_b32_e32 v66, 0
	v_mov_b32_e32 v67, 0
	s_add_i32 m0, s3, 0x0
	s_nop 0
	global_load_lds_dwordx4 v68, s[98:99]
	s_add_i32 m0, s3, 0x1000
	s_nop 0
	global_load_lds_dwordx4 v69, s[98:99]
	s_add_i32 m0, s3, 0x2000
	s_nop 0
	global_load_lds_dwordx4 v70, s[98:99]
	s_add_i32 m0, s3, 0x3000
	s_nop 0
	global_load_lds_dwordx4 v71, s[98:99]
	s_add_i32 m0, s3, 0x4000
	s_nop 0
	global_load_lds_dwordx4 v68, s[100:101]
	s_add_i32 m0, s3, 0x5000
	s_nop 0
	global_load_lds_dwordx4 v69, s[100:101]
	s_add_i32 m0, s3, 0x6000
	s_nop 0
	global_load_lds_dwordx4 v70, s[100:101]
	s_add_i32 m0, s3, 0x7000
	s_nop 0
	global_load_lds_dwordx4 v71, s[100:101]
	s_add_u32 s98, s98, 0x80
	s_addc_u32 s99, s99, 0
	s_add_u32 s100, s100, 0x80
	s_addc_u32 s101, s101, 0
	s_waitcnt vmcnt(0)
	s_waitcnt lgkmcnt(0)
	s_barrier
	s_add_i32 m0, s3, 0x8000
	s_nop 0
	global_load_lds_dwordx4 v68, s[98:99]
	s_add_i32 m0, s3, 0x9000
	s_nop 0
	global_load_lds_dwordx4 v69, s[98:99]
	s_add_i32 m0, s3, 0xa000
	s_nop 0
	global_load_lds_dwordx4 v70, s[98:99]
	s_add_i32 m0, s3, 0xb000
	s_nop 0
	global_load_lds_dwordx4 v71, s[98:99]
	s_add_i32 m0, s3, 0xc000
	s_nop 0
	global_load_lds_dwordx4 v68, s[100:101]
	s_add_i32 m0, s3, 0xd000
	s_nop 0
	global_load_lds_dwordx4 v69, s[100:101]
	s_add_i32 m0, s3, 0xe000
	s_nop 0
	global_load_lds_dwordx4 v70, s[100:101]
	s_add_i32 m0, s3, 0xf000
	s_nop 0
	global_load_lds_dwordx4 v71, s[100:101]
	s_add_u32 s98, s98, 0x80
	s_addc_u32 s99, s99, 0
	s_add_u32 s100, s100, 0x80
	s_addc_u32 s101, s101, 0
	ds_read_b128 v[102:105], v238
	ds_read_b128 v[106:109], v238 offset:4096
	ds_read_b128 v[110:113], v80
	ds_read_b128 v[114:117], v80 offset:4096
	ds_read_b128 v[118:121], v239
	ds_read_b128 v[122:125], v239 offset:4096
	ds_read_b128 v[126:129], v81
	ds_read_b128 v[130:133], v81 offset:4096
	ds_read_b128 v[134:137], v240
	ds_read_b128 v[138:141], v240 offset:4096
	ds_read_b128 v[142:145], v98
	ds_read_b128 v[146:149], v98 offset:4096
	ds_read_b128 v[150:153], v241
	ds_read_b128 v[154:157], v241 offset:4096
	ds_read_b128 v[158:161], v100
	ds_read_b128 v[162:165], v100 offset:4096
	s_movk_i32 s2, 7
; #define MFMA32(a, b, c) __builtin_amdgcn_mfma_f32_32x32x16_bf16((a), (b), (c), 0, 0, 0)
; template <int MF, int BK, class Epi>
; DI void gemm_phase_t(char* lds, const GemmDesc g, const Epi epi) {
;     ...
;     for (int kt = 0; kt < nk; ++kt) {
;       __syncthreads();
;       const u16* sA = sbase + (kt & 1) * STG;
;       const u16* sB = sA + BM * LS;
;       if (kt + 1 < nk) {
;         u16* nA = sbase + ((kt + 1) & 1) * STG;
; #pragma unroll
;         for (int j = 0; j < APT; ++j) *(u32x4*)(nA + (lr + RSTEP * j) * LS + lc * 8) = ra[j];
; #pragma unroll
;         for (int j = 0; j < BPT; ++j) *(u32x4*)(nA + BM * LS + (lr + RSTEP * j) * LS + lc * 8) = rb[j];
;         if (kt + 2 < nk) {
; #pragma unroll
;           for (int j = 0; j < APT; ++j) ra[j] = *(const u32x4*)(Ap + (size_t)j * RSTEP * g.lda + (kt + 2) * BK);
; #pragma unroll
;           for (int j = 0; j < BPT; ++j) rb[j] = *(const u32x4*)(Bp + (size_t)j * RSTEP * g.ldb + (kt + 2) * BK);
;         }
;       }
;       bf16x8 af[NKK][MF], bfr[NKK][2];
; #pragma unroll
;       for (int kk = 0; kk < NKK; ++kk) {
; #pragma unroll
;         for (int ni = 0; ni < 2; ++ni) bfr[kk][ni] = *(const bf16x8*)(sB + (wn * 64 + ni * 32 + l31) * LS + kk * 16 + h * 8);
; #pragma unroll
;         for (int mi = 0; mi < MF; ++mi) af[kk][mi] = *(const bf16x8*)(sA + (wm * (MF * 32) + mi * 32 + l31) * LS + kk * 16 + h * 8);
;       }
;       __builtin_amdgcn_sched_barrier(0);
; #pragma unroll
;       for (int kk = 0; kk < NKK; ++kk)
; #pragma unroll
;         for (int mi = 0; mi < MF; ++mi)
; #pragma unroll
;           for (int ni = 0; ni < 2; ++ni) acc[mi][ni] = MFMA32(bfr[kk][ni], af[kk][mi], acc[mi][ni]);
.Ldma_oi_loop:
	s_waitcnt vmcnt(0)
	s_waitcnt lgkmcnt(0)
	s_barrier
	s_add_i32 m0, s3, 0x0
	s_nop 0
	global_load_lds_dwordx4 v68, s[98:99]
	s_add_i32 m0, s3, 0x1000
	s_nop 0
	global_load_lds_dwordx4 v69, s[98:99]
	s_add_i32 m0, s3, 0x2000
	s_nop 0
	global_load_lds_dwordx4 v70, s[98:99]
	s_add_i32 m0, s3, 0x3000
	s_nop 0
	global_load_lds_dwordx4 v71, s[98:99]
	s_add_i32 m0, s3, 0x4000
	s_nop 0
	global_load_lds_dwordx4 v68, s[100:101]
	s_add_i32 m0, s3, 0x5000
	s_nop 0
	global_load_lds_dwordx4 v69, s[100:101]
	s_add_i32 m0, s3, 0x6000
	s_nop 0
	global_load_lds_dwordx4 v70, s[100:101]
	s_add_i32 m0, s3, 0x7000
	s_nop 0
	global_load_lds_dwordx4 v71, s[100:101]
	s_add_u32 s98, s98, 0x80
	s_addc_u32 s99, s99, 0
	s_add_u32 s100, s100, 0x80
	s_addc_u32 s101, s101, 0
	ds_read_b128 v[168:171], v238 offset:32768
	ds_read_b128 v[172:175], v238 offset:36864
	ds_read_b128 v[176:179], v80 offset:32768
	ds_read_b128 v[180:183], v80 offset:36864
	ds_read_b128 v[184:187], v239 offset:32768
	ds_read_b128 v[188:191], v239 offset:36864
	ds_read_b128 v[192:195], v81 offset:32768
	ds_read_b128 v[204:207], v81 offset:36864
	ds_read_b128 v[82:85], v240 offset:32768
	ds_read_b128 v[86:89], v240 offset:36864
	ds_read_b128 v[90:93], v98 offset:32768
	ds_read_b128 v[218:221], v98 offset:36864
	ds_read_b128 v[222:225], v241 offset:32768
	ds_read_b128 v[226:229], v241 offset:36864
	ds_read_b128 v[230:233], v100 offset:32768
	ds_read_b128 v[234:237], v100 offset:36864
	v_mfma_f32_32x32x16_bf16 v[52:67], v[102:105], v[110:113], v[52:67]
	v_mfma_f32_32x32x16_bf16 v[36:51], v[106:109], v[110:113], v[36:51]
	v_mfma_f32_32x32x16_bf16 v[20:35], v[102:105], v[114:117], v[20:35]
	v_mfma_f32_32x32x16_bf16 v[4:19], v[106:109], v[114:117], v[4:19]
	v_mfma_f32_32x32x16_bf16 v[52:67], v[118:121], v[126:129], v[52:67]
	v_mfma_f32_32x32x16_bf16 v[36:51], v[122:125], v[126:129], v[36:51]
	v_mfma_f32_32x32x16_bf16 v[20:35], v[118:121], v[130:133], v[20:35]
	v_mfma_f32_32x32x16_bf16 v[4:19], v[122:125], v[130:133], v[4:19]
	v_mfma_f32_32x32x16_bf16 v[52:67], v[134:137], v[142:145], v[52:67]
	v_mfma_f32_32x32x16_bf16 v[36:51], v[138:141], v[142:145], v[36:51]
	v_mfma_f32_32x32x16_bf16 v[20:35], v[134:137], v[146:149], v[20:35]
	v_mfma_f32_32x32x16_bf16 v[4:19], v[138:141], v[146:149], v[4:19]
	v_mfma_f32_32x32x16_bf16 v[52:67], v[150:153], v[158:161], v[52:67]
	v_mfma_f32_32x32x16_bf16 v[36:51], v[154:157], v[158:161], v[36:51]
	v_mfma_f32_32x32x16_bf16 v[20:35], v[150:153], v[162:165], v[20:35]
	v_mfma_f32_32x32x16_bf16 v[4:19], v[154:157], v[162:165], v[4:19]
	s_waitcnt vmcnt(0)
	s_waitcnt lgkmcnt(0)
	s_barrier
	s_add_i32 m0, s3, 0x8000
	s_nop 0
	global_load_lds_dwordx4 v68, s[98:99]
	s_add_i32 m0, s3, 0x9000
	s_nop 0
	global_load_lds_dwordx4 v69, s[98:99]
	s_add_i32 m0, s3, 0xa000
	s_nop 0
	global_load_lds_dwordx4 v70, s[98:99]
	s_add_i32 m0, s3, 0xb000
	s_nop 0
	global_load_lds_dwordx4 v71, s[98:99]
	s_add_i32 m0, s3, 0xc000
	s_nop 0
	global_load_lds_dwordx4 v68, s[100:101]
	s_add_i32 m0, s3, 0xd000
	s_nop 0
	global_load_lds_dwordx4 v69, s[100:101]
	s_add_i32 m0, s3, 0xe000
	s_nop 0
	global_load_lds_dwordx4 v70, s[100:101]
	s_add_i32 m0, s3, 0xf000
	s_nop 0
	global_load_lds_dwordx4 v71, s[100:101]
	s_add_u32 s98, s98, 0x80
	s_addc_u32 s99, s99, 0
	s_add_u32 s100, s100, 0x80
	s_addc_u32 s101, s101, 0
	ds_read_b128 v[102:105], v238
	ds_read_b128 v[106:109], v238 offset:4096
	ds_read_b128 v[110:113], v80
	ds_read_b128 v[114:117], v80 offset:4096
	ds_read_b128 v[118:121], v239
	ds_read_b128 v[122:125], v239 offset:4096
	ds_read_b128 v[126:129], v81
	ds_read_b128 v[130:133], v81 offset:4096
	ds_read_b128 v[134:137], v240
	ds_read_b128 v[138:141], v240 offset:4096
	ds_read_b128 v[142:145], v98
	ds_read_b128 v[146:149], v98 offset:4096
	ds_read_b128 v[150:153], v241
	ds_read_b128 v[154:157], v241 offset:4096
	ds_read_b128 v[158:161], v100
	ds_read_b128 v[162:165], v100 offset:4096
	v_mfma_f32_32x32x16_bf16 v[52:67], v[168:171], v[176:179], v[52:67]
	v_mfma_f32_32x32x16_bf16 v[36:51], v[172:175], v[176:179], v[36:51]
	v_mfma_f32_32x32x16_bf16 v[20:35], v[168:171], v[180:183], v[20:35]
	v_mfma_f32_32x32x16_bf16 v[4:19], v[172:175], v[180:183], v[4:19]
	v_mfma_f32_32x32x16_bf16 v[52:67], v[184:187], v[192:195], v[52:67]
	v_mfma_f32_32x32x16_bf16 v[36:51], v[188:191], v[192:195], v[36:51]
	v_mfma_f32_32x32x16_bf16 v[20:35], v[184:187], v[204:207], v[20:35]
	v_mfma_f32_32x32x16_bf16 v[4:19], v[188:191], v[204:207], v[4:19]
	v_mfma_f32_32x32x16_bf16 v[52:67], v[82:85], v[90:93], v[52:67]
	v_mfma_f32_32x32x16_bf16 v[36:51], v[86:89], v[90:93], v[36:51]
	v_mfma_f32_32x32x16_bf16 v[20:35], v[82:85], v[218:221], v[20:35]
	v_mfma_f32_32x32x16_bf16 v[4:19], v[86:89], v[218:221], v[4:19]
	v_mfma_f32_32x32x16_bf16 v[52:67], v[222:225], v[230:233], v[52:67]
	v_mfma_f32_32x32x16_bf16 v[36:51], v[226:229], v[230:233], v[36:51]
	v_mfma_f32_32x32x16_bf16 v[20:35], v[222:225], v[234:237], v[20:35]
	v_mfma_f32_32x32x16_bf16 v[4:19], v[226:229], v[234:237], v[4:19]
	s_add_i32 s2, s2, -1
	s_cmp_lg_u32 s2, 0
	s_cbranch_scc1 .Ldma_oi_loop
	s_waitcnt vmcnt(0)
	s_waitcnt lgkmcnt(0)
	s_barrier
; template <int MF, int BK, class Epi>
; DI void gemm_phase_t(char* lds, const GemmDesc g, const Epi epi) {
;     ...
;     for (int kt = 0; kt < nk; ++kt) {
;       __syncthreads();
;       const u16* sA = sbase + (kt & 1) * STG;
;       const u16* sB = sA + BM * LS;
;       if (kt + 1 < nk) {
;         u16* nA = sbase + ((kt + 1) & 1) * STG;
; #pragma unroll
;         for (int j = 0; j < APT; ++j) *(u32x4*)(nA + (lr + RSTEP * j) * LS + lc * 8) = ra[j];
; #pragma unroll
;         for (int j = 0; j < BPT; ++j) *(u32x4*)(nA + BM * LS + (lr + RSTEP * j) * LS + lc * 8) = rb[j];
;         if (kt + 2 < nk) {
; #pragma unroll
;           for (int j = 0; j < APT; ++j) ra[j] = *(const u32x4*)(Ap + (size_t)j * RSTEP * g.lda + (kt + 2) * BK);
; #pragma unroll
;           for (int j = 0; j < BPT; ++j) rb[j] = *(const u32x4*)(Bp + (size_t)j * RSTEP * g.ldb + (kt + 2) * BK);
;         }
;       }
;       bf16x8 af[NKK][MF], bfr[NKK][2];
; #pragma unroll
;       for (int kk = 0; kk < NKK; ++kk) {
; #pragma unroll
;         for (int ni = 0; ni < 2; ++ni) bfr[kk][ni] = *(const bf16x8*)(sB + (wn * 64 + ni * 32 + l31) * LS + kk * 16 + h * 8);
; #pragma unroll
;         for (int mi = 0; mi < MF; ++mi) af[kk][mi] = *(const bf16x8*)(sA + (wm * (MF * 32) + mi * 32 + l31) * LS + kk * 16 + h * 8);
;       }
;       __builtin_amdgcn_sched_barrier(0);
; #pragma unroll
;       for (int kk = 0; kk < NKK; ++kk)
; #pragma unroll
;         for (int mi = 0; mi < MF; ++mi)
; #pragma unroll
;           for (int ni = 0; ni < 2; ++ni) acc[mi][ni] = MFMA32(bfr[kk][ni], af[kk][mi], acc[mi][ni]);
;   template <int MF> DI void operator()(f32x16 (&acc)[MF][2], int mb, int nb, int l31, int h) const {
;     if (nb >= 1024) {
; #pragma unroll
;       for (int mi = 0; mi < MF; ++mi) {
;         const int row = mb + mi * 32 + l31;
; #pragma unroll
;         for (int g4 = 0; g4 < 4; ++g4) {
;           const int col0 = nb + 16 * g4 + 8 * h;
;           if (col0 < 1952) *(u32x4*)(z + (size_t)row * 1952 + col0) = (u32x4){pack2(acc[mi][0][4 * g4], acc[mi][0][4 * g4 + 1]), pack2(acc[mi][0][4 * g4 + 2], acc[mi][0][4 * g4 + 3]),
;                                                                                 pack2(acc[mi][1][4 * g4], acc[mi][1][4 * g4 + 1]), pack2(acc[mi][1][4 * g4 + 2], acc[mi][1][4 * g4 + 3])};
;         }
;       }
;       return;
;     }
	ds_read_b128 v[168:171], v238 offset:32768
	ds_read_b128 v[172:175], v238 offset:36864
	ds_read_b128 v[176:179], v80 offset:32768
	ds_read_b128 v[180:183], v80 offset:36864
	ds_read_b128 v[184:187], v239 offset:32768
	ds_read_b128 v[188:191], v239 offset:36864
	ds_read_b128 v[192:195], v81 offset:32768
	ds_read_b128 v[204:207], v81 offset:36864
	ds_read_b128 v[82:85], v240 offset:32768
	ds_read_b128 v[86:89], v240 offset:36864
	ds_read_b128 v[90:93], v98 offset:32768
	ds_read_b128 v[218:221], v98 offset:36864
	ds_read_b128 v[222:225], v241 offset:32768
	ds_read_b128 v[226:229], v241 offset:36864
	ds_read_b128 v[230:233], v100 offset:32768
	ds_read_b128 v[234:237], v100 offset:36864
	v_mfma_f32_32x32x16_bf16 v[52:67], v[102:105], v[110:113], v[52:67]
	v_mfma_f32_32x32x16_bf16 v[36:51], v[106:109], v[110:113], v[36:51]
	v_mfma_f32_32x32x16_bf16 v[20:35], v[102:105], v[114:117], v[20:35]
	v_mfma_f32_32x32x16_bf16 v[4:19], v[106:109], v[114:117], v[4:19]
	v_mfma_f32_32x32x16_bf16 v[52:67], v[118:121], v[126:129], v[52:67]
	v_mfma_f32_32x32x16_bf16 v[36:51], v[122:125], v[126:129], v[36:51]
	v_mfma_f32_32x32x16_bf16 v[20:35], v[118:121], v[130:133], v[20:35]
	v_mfma_f32_32x32x16_bf16 v[4:19], v[122:125], v[130:133], v[4:19]
	v_mfma_f32_32x32x16_bf16 v[52:67], v[134:137], v[142:145], v[52:67]
	v_mfma_f32_32x32x16_bf16 v[36:51], v[138:141], v[142:145], v[36:51]
	v_mfma_f32_32x32x16_bf16 v[20:35], v[134:137], v[146:149], v[20:35]
	v_mfma_f32_32x32x16_bf16 v[4:19], v[138:141], v[146:149], v[4:19]
	v_mfma_f32_32x32x16_bf16 v[52:67], v[150:153], v[158:161], v[52:67]
	v_mfma_f32_32x32x16_bf16 v[36:51], v[154:157], v[158:161], v[36:51]
	v_mfma_f32_32x32x16_bf16 v[20:35], v[150:153], v[162:165], v[20:35]
	v_mfma_f32_32x32x16_bf16 v[4:19], v[154:157], v[162:165], v[4:19]
	s_waitcnt lgkmcnt(0)
	v_mfma_f32_32x32x16_bf16 v[52:67], v[168:171], v[176:179], v[52:67]
	v_mfma_f32_32x32x16_bf16 v[36:51], v[172:175], v[176:179], v[36:51]
	v_mfma_f32_32x32x16_bf16 v[20:35], v[168:171], v[180:183], v[20:35]
	v_mfma_f32_32x32x16_bf16 v[4:19], v[172:175], v[180:183], v[4:19]
	v_mfma_f32_32x32x16_bf16 v[52:67], v[184:187], v[192:195], v[52:67]
	v_mfma_f32_32x32x16_bf16 v[36:51], v[188:191], v[192:195], v[36:51]
	v_mfma_f32_32x32x16_bf16 v[20:35], v[184:187], v[204:207], v[20:35]
	v_mfma_f32_32x32x16_bf16 v[4:19], v[188:191], v[204:207], v[4:19]
	v_mfma_f32_32x32x16_bf16 v[52:67], v[82:85], v[90:93], v[52:67]
	v_mfma_f32_32x32x16_bf16 v[36:51], v[86:89], v[90:93], v[36:51]
	v_mfma_f32_32x32x16_bf16 v[20:35], v[82:85], v[218:221], v[20:35]
	v_mfma_f32_32x32x16_bf16 v[4:19], v[86:89], v[218:221], v[4:19]
	v_mfma_f32_32x32x16_bf16 v[52:67], v[222:225], v[230:233], v[52:67]
	v_mfma_f32_32x32x16_bf16 v[36:51], v[226:229], v[230:233], v[36:51]
	v_mfma_f32_32x32x16_bf16 v[20:35], v[222:225], v[234:237], v[20:35]
	v_mfma_f32_32x32x16_bf16 v[4:19], v[226:229], v[234:237], v[4:19]
	v_add_u32_e32 v70, s21, v95
	v_add_u32_e32 v89, s0, v96
	s_movk_i32 s0, 0x400
	v_cmp_gt_i32_e32 vcc, s0, v70
	v_or_b32_e32 v88, v89, v77
	s_and_saveexec_b64 s[0:1], vcc
	s_xor_b64 s[12:13], exec, s[0:1]
	s_cbranch_execz .LBB0_932
	s_movk_i32 s0, 0x7fff
	s_mov_b32 s2, 0x8000
	s_movk_i32 s14, 0xfdf
	v_cmp_lt_i32_e64 s[0:1], s0, v88
	v_cmp_gt_i32_e64 s[2:3], s2, v88
	v_bitop3_b32 v90, v89, s14, v77 bitop3:0xc8
	v_and_b32_e32 v82, 0xfc0, v89
	s_and_saveexec_b64 s[14:15], s[2:3]
	s_cbranch_execz .LBB0_913
	v_lshlrev_b32_e32 v2, 6, v90
	v_mov_b32_e32 v83, v3
	v_and_b32_e32 v2, 0x7c0, v2
	v_lshl_add_u64 v[68:69], v[78:79], 0, v[82:83]
	v_lshl_add_u64 v[86:87], v[78:79], 0, v[2:3]
	s_mov_b64 s[16:17], 0x1000
	v_lshl_add_u64 v[70:71], v[68:69], 0, s[16:17]
	v_lshl_add_u64 v[92:93], v[86:87], 0, s[16:17]
	s_movk_i32 s16, 0x1000
	global_load_dwordx4 v[102:105], v[68:69], off offset:16
	global_load_dwordx4 v[106:109], v[68:69], off
	v_add_co_u32_e32 v68, vcc, s16, v68
	s_nop 1
	v_addc_co_u32_e32 v69, vcc, 0, v69, vcc
	global_load_dwordx4 v[110:113], v[68:69], off
	global_load_dwordx4 v[114:117], v[70:71], off offset:16
	s_waitcnt vmcnt(2)
	v_pk_mul_f32 v[68:69], v[56:57], v[106:107]
	s_waitcnt vmcnt(1)
	v_pk_mul_f32 v[56:57], v[56:57], v[110:111]
	v_pk_fma_f32 v[84:85], v[52:53], v[110:111], v[68:69] neg_lo:[0,0,1] neg_hi:[0,0,1]
	v_pk_fma_f32 v[56:57], v[52:53], v[106:107], v[56:57]
	global_load_dwordx4 v[68:71], v[86:87], off offset:16
	global_load_dwordx4 v[118:121], v[86:87], off
	v_add_co_u32_e32 v52, vcc, s16, v86
	s_nop 1
	v_addc_co_u32_e32 v53, vcc, 0, v87, vcc
	global_load_dwordx4 v[122:125], v[52:53], off
	global_load_dwordx4 v[126:129], v[92:93], off offset:16
	s_waitcnt vmcnt(2)
	v_pk_mul_f32 v[52:53], v[64:65], v[118:119]
	s_waitcnt vmcnt(1)
	v_pk_fma_f32 v[86:87], v[60:61], v[122:123], v[52:53] neg_lo:[0,0,1] neg_hi:[0,0,1]
	v_pk_mul_f32 v[52:53], v[64:65], v[122:123]
	s_nop 0
	v_pk_fma_f32 v[64:65], v[60:61], v[118:119], v[52:53]
	v_pk_mul_f32 v[52:53], v[58:59], v[108:109]
	v_pk_mul_f32 v[58:59], v[58:59], v[112:113]
	v_pk_fma_f32 v[52:53], v[54:55], v[112:113], v[52:53] neg_lo:[0,0,1] neg_hi:[0,0,1]
	v_pk_fma_f32 v[58:59], v[54:55], v[108:109], v[58:59]
	v_pk_mul_f32 v[54:55], v[66:67], v[120:121]
	s_nop 0
	v_pk_fma_f32 v[60:61], v[62:63], v[124:125], v[54:55] neg_lo:[0,0,1] neg_hi:[0,0,1]
	v_pk_mul_f32 v[54:55], v[66:67], v[124:125]
	s_nop 0
	v_pk_fma_f32 v[66:67], v[62:63], v[120:121], v[54:55]
	v_pk_mul_f32 v[54:55], v[40:41], v[102:103]
	v_pk_mul_f32 v[40:41], v[40:41], v[114:115]
	v_pk_fma_f32 v[54:55], v[36:37], v[114:115], v[54:55] neg_lo:[0,0,1] neg_hi:[0,0,1]
	v_pk_fma_f32 v[40:41], v[36:37], v[102:103], v[40:41]
	v_pk_mul_f32 v[36:37], v[48:49], v[68:69]
	s_waitcnt vmcnt(0)
	v_pk_fma_f32 v[62:63], v[44:45], v[126:127], v[36:37] neg_lo:[0,0,1] neg_hi:[0,0,1]
	v_pk_mul_f32 v[36:37], v[48:49], v[126:127]
	s_nop 0
	v_pk_fma_f32 v[48:49], v[44:45], v[68:69], v[36:37]
	v_pk_mul_f32 v[36:37], v[42:43], v[104:105]
	v_pk_mul_f32 v[42:43], v[42:43], v[116:117]
	v_pk_fma_f32 v[36:37], v[38:39], v[116:117], v[36:37] neg_lo:[0,0,1] neg_hi:[0,0,1]
	v_pk_fma_f32 v[42:43], v[38:39], v[104:105], v[42:43]
	v_pk_mul_f32 v[38:39], v[50:51], v[70:71]
	s_nop 0
	v_pk_fma_f32 v[44:45], v[46:47], v[128:129], v[38:39] neg_lo:[0,0,1] neg_hi:[0,0,1]
	v_pk_mul_f32 v[38:39], v[50:51], v[128:129]
	s_nop 0
	v_pk_fma_f32 v[50:51], v[46:47], v[70:71], v[38:39]
	v_mov_b32_e32 v38, v36
	v_mov_b32_e32 v39, v37
	v_mov_b32_e32 v36, v54
	v_mov_b32_e32 v37, v55
	v_mov_b32_e32 v54, v52
	v_mov_b32_e32 v55, v53
	v_mov_b32_e32 v52, v84
	v_mov_b32_e32 v53, v85
	v_mov_b32_e32 v46, v44
	v_mov_b32_e32 v47, v45
	v_mov_b32_e32 v44, v62
	v_mov_b32_e32 v45, v63
	v_mov_b32_e32 v62, v60
	v_mov_b32_e32 v63, v61
	v_mov_b32_e32 v60, v86
	v_mov_b32_e32 v61, v87
